# aligned combo12 + phase-start serial-latency trims: one ds_read2 for the two phase-header LDS words, IN post-prologue drain removed, MG redundant zeroing off the K-loop path
# speedup vs baseline: 1.0003x; 1.0003x over previous
; #define LAS __attribute__((address_space(3)))
; __global__ void __launch_bounds__(NWAVES * 64, 2) fwd_kernel(Args args) {
;     ...
;         { int tv = threadIdx.x; asm volatile("" : "+v"(tv)); F.tid = tv; F.lane = tv & 63; F.wave = __builtin_amdgcn_readfirstlane(tv >> 6); }
;         int moff = MISC_OFF; asm volatile("" : "+s"(moff));
;         const volatile LAS unsigned* mw = (const volatile LAS unsigned*)(F.lds + moff);
;         const int bal = __builtin_amdgcn_readfirstlane((int)mw[11]);
;         const int cid = bal ? __builtin_amdgcn_readfirstlane((int)mw[10]) * 8 + (int)bar.x : (int)blockIdx.x;
;         F.vcu = (F.G % 8 == 0) ? (cid % 8) * (F.G / 8) + cid / 8 : cid;
.LBB0_21:
	v_mov_b32_e32 v250, v0
	s_mov_b32 s0, 0x20140
	s_add_i32 s1, s0, 0
	v_mov_b32_e32 v2, s1
	ds_read2_b32 v[4:5], v2 offset0:10 offset1:11
	v_readfirstlane_b32 s0, v250
	s_mov_b32 s50, s86
	s_waitcnt lgkmcnt(0)
	v_readfirstlane_b32 s2, v5
	s_cmp_lg_u32 s2, 0
	s_cselect_b64 s[36:37], -1, 0
	s_cmp_eq_u32 s2, 0
	s_cselect_b64 s[2:3], -1, 0
	v_writelane_b32 v254, s2, 48
	s_and_b64 vcc, exec, s[2:3]
	s_nop 0
	v_writelane_b32 v254, s3, 49
	s_cbranch_vccnz .LBB0_23
	v_readfirstlane_b32 s1, v4
	s_lshl_b32 s1, s1, 3
	s_add_i32 s50, s1, s88

; template <class Epi, class Sched, bool ALIGN_EPI = false, bool SP2 = false, bool ACHUNK = false>
; __device__ __forceinline__ void gemm_phase(PG8_LAS unsigned char* lds, const Gemm g, const Sched& S, const Epi& E) {
;     ...
;         const bool has_next = S.next(ui + 1, nxt);
;         const char* nA = has_next ? (const char*)g.A + (size_t)nxt.pm * tstepA : cA; const char* nB = has_next ? (const char*)g.Bt + (size_t)nxt.pn * tstepB : cB;
;         for (int t = 0; t < nt; t += 2) {
;             const bool last = (t == nt - 2);
;             if constexpr (Epi::HAS_MID) { if (t == Epi::MID_T) E.mid(acc, cur, wr, wc, fr, fq, ShflDev{}); }
;     ...
;         if (!has_next) break;
;         if constexpr (Epi::HAS_INIT) E.init(acc, nxt, wr, wc, fr, fq);
;         else {
; #pragma unroll
;         for (int a = 0; a < 2; ++a)
; #pragma unroll
;             for (int b = 0; b < 2; ++b)
; #pragma unroll
;                 for (int m = 0; m < 4; ++m)
; #pragma unroll
;                     for (int n = 0; n < 2; ++n) acc[a][b][m][n] = (f32x4){0.f, 0.f, 0.f, 0.f};
;         }
;         cur = nxt; cA = nA; cB = nB; ++ui;
.LBB0_264:
	s_nop 0
	s_andn2_b64 vcc, exec, s[30:31]
	s_cbranch_vccnz .Lmg_zero_stub
	s_lshl_b32 s8, s46, 8
	s_lshl_b32 s48, s45, 8
	s_or_b32 s47, s8, s25
	s_add_i32 s48, s48, s24
	s_add_u32 s49, s6, 0x100
	s_addc_u32 s50, s7, 0
	s_add_u32 s6, s4, 0x80
	v_mov_b32_e32 v4, v3
	v_mov_b32_e32 v5, v3
	s_addc_u32 s7, s5, 0
	v_mov_b32_e32 v2, v3
	v_mov_b64_e32 v[8:9], v[4:5]
	v_mov_b64_e32 v[12:13], v[4:5]
	v_mov_b64_e32 v[24:25], v[4:5]
	v_mov_b64_e32 v[28:29], v[4:5]
	v_mov_b64_e32 v[40:41], v[4:5]
	v_mov_b64_e32 v[44:45], v[4:5]
	v_mov_b64_e32 v[56:57], v[4:5]
	v_mov_b64_e32 v[60:61], v[4:5]
	v_mov_b64_e32 v[16:17], v[4:5]
	v_mov_b64_e32 v[20:21], v[4:5]
	v_mov_b64_e32 v[32:33], v[4:5]
	v_mov_b64_e32 v[36:37], v[4:5]
	v_mov_b64_e32 v[48:49], v[4:5]
	v_mov_b64_e32 v[52:53], v[4:5]
	v_mov_b64_e32 v[64:65], v[4:5]
	v_mov_b64_e32 v[68:69], v[4:5]
	v_mov_b64_e32 v[72:73], v[4:5]
	v_mov_b64_e32 v[76:77], v[4:5]
	v_mov_b64_e32 v[88:89], v[4:5]
	v_mov_b64_e32 v[92:93], v[4:5]
	v_mov_b64_e32 v[104:105], v[4:5]
	v_mov_b64_e32 v[108:109], v[4:5]
	v_mov_b64_e32 v[120:121], v[4:5]
	v_mov_b64_e32 v[124:125], v[4:5]
	v_mov_b64_e32 v[80:81], v[4:5]
	v_mov_b64_e32 v[84:85], v[4:5]
	v_mov_b64_e32 v[96:97], v[4:5]
	v_mov_b64_e32 v[100:101], v[4:5]
	v_mov_b64_e32 v[112:113], v[4:5]
	v_mov_b64_e32 v[116:117], v[4:5]
	v_mov_b64_e32 v[132:133], v[4:5]
	v_mov_b64_e32 v[128:129], v[4:5]
	v_lshl_add_u64 v[210:211], s[6:7], 0, v[206:207]
	v_lshl_add_u64 v[212:213], s[6:7], 0, v[208:209]
	s_mov_b32 s8, 0
	s_mov_b64 s[6:7], 0
	v_mov_b64_e32 v[6:7], v[2:3]
	v_mov_b64_e32 v[10:11], v[2:3]
	v_mov_b64_e32 v[22:23], v[2:3]
	v_mov_b64_e32 v[26:27], v[2:3]
	v_mov_b64_e32 v[38:39], v[2:3]
	v_mov_b64_e32 v[42:43], v[2:3]
	v_mov_b64_e32 v[54:55], v[2:3]
	v_mov_b64_e32 v[58:59], v[2:3]
	v_mov_b64_e32 v[14:15], v[2:3]
	v_mov_b64_e32 v[18:19], v[2:3]
	v_mov_b64_e32 v[30:31], v[2:3]
	v_mov_b64_e32 v[34:35], v[2:3]
	v_mov_b64_e32 v[46:47], v[2:3]
	v_mov_b64_e32 v[50:51], v[2:3]
	v_mov_b64_e32 v[62:63], v[2:3]
	v_mov_b64_e32 v[66:67], v[2:3]
	v_mov_b64_e32 v[70:71], v[2:3]
	v_mov_b64_e32 v[74:75], v[2:3]
	v_mov_b64_e32 v[86:87], v[2:3]
	v_mov_b64_e32 v[90:91], v[2:3]
	v_mov_b64_e32 v[102:103], v[2:3]
	v_mov_b64_e32 v[106:107], v[2:3]
	v_mov_b64_e32 v[118:119], v[2:3]
	v_mov_b64_e32 v[122:123], v[2:3]
	v_mov_b64_e32 v[78:79], v[2:3]
	v_mov_b64_e32 v[82:83], v[2:3]
	v_mov_b64_e32 v[94:95], v[2:3]
	v_mov_b64_e32 v[98:99], v[2:3]
	v_mov_b64_e32 v[110:111], v[2:3]
	v_mov_b64_e32 v[114:115], v[2:3]
	v_mov_b64_e32 v[130:131], v[2:3]
	v_mov_b64_e32 v[126:127], v[2:3]
	s_cmp_lg_u32 s8, 8
	s_cbranch_scc1 .LBB0_268
	s_branch .LBB0_267
.Lmg_zero_stub:
	v_mov_b32_e32 v129, 0
	v_mov_b32_e32 v128, 0
	v_mov_b32_e32 v127, 0
	v_mov_b32_e32 v126, 0
	v_mov_b32_e32 v133, 0
	v_mov_b32_e32 v132, 0
	v_mov_b32_e32 v131, 0
	v_mov_b32_e32 v130, 0
	v_mov_b32_e32 v117, 0
	v_mov_b32_e32 v116, 0
	v_mov_b32_e32 v115, 0
	v_mov_b32_e32 v114, 0
	v_mov_b32_e32 v113, 0
	v_mov_b32_e32 v112, 0
	v_mov_b32_e32 v111, 0
	v_mov_b32_e32 v110, 0
	v_mov_b32_e32 v101, 0
	v_mov_b32_e32 v100, 0
	v_mov_b32_e32 v99, 0
	v_mov_b32_e32 v98, 0
	v_mov_b32_e32 v97, 0
	v_mov_b32_e32 v96, 0
	v_mov_b32_e32 v95, 0
	v_mov_b32_e32 v94, 0
	v_mov_b32_e32 v85, 0
	v_mov_b32_e32 v84, 0
	v_mov_b32_e32 v83, 0
	v_mov_b32_e32 v82, 0
	v_mov_b32_e32 v81, 0
	v_mov_b32_e32 v80, 0
	v_mov_b32_e32 v79, 0
	v_mov_b32_e32 v78, 0
	v_mov_b32_e32 v125, 0
	v_mov_b32_e32 v124, 0
	v_mov_b32_e32 v123, 0
	v_mov_b32_e32 v122, 0
	v_mov_b32_e32 v121, 0
	v_mov_b32_e32 v120, 0
	v_mov_b32_e32 v119, 0
	v_mov_b32_e32 v118, 0
	v_mov_b32_e32 v109, 0
	v_mov_b32_e32 v108, 0
	v_mov_b32_e32 v107, 0
	v_mov_b32_e32 v106, 0
	v_mov_b32_e32 v105, 0
	v_mov_b32_e32 v104, 0
	v_mov_b32_e32 v103, 0
	v_mov_b32_e32 v102, 0
	v_mov_b32_e32 v93, 0
	v_mov_b32_e32 v92, 0
	v_mov_b32_e32 v91, 0
	v_mov_b32_e32 v90, 0
	v_mov_b32_e32 v89, 0
	v_mov_b32_e32 v88, 0
	v_mov_b32_e32 v87, 0
	v_mov_b32_e32 v86, 0
	v_mov_b32_e32 v77, 0
	v_mov_b32_e32 v76, 0
	v_mov_b32_e32 v75, 0
	v_mov_b32_e32 v74, 0
	v_mov_b32_e32 v73, 0
	v_mov_b32_e32 v72, 0
	v_mov_b32_e32 v71, 0
	v_mov_b32_e32 v70, 0
	v_mov_b32_e32 v69, 0
	v_mov_b32_e32 v68, 0
	v_mov_b32_e32 v67, 0
	v_mov_b32_e32 v66, 0
	v_mov_b32_e32 v65, 0
	v_mov_b32_e32 v64, 0
	v_mov_b32_e32 v63, 0
	v_mov_b32_e32 v62, 0
	v_mov_b32_e32 v53, 0
	v_mov_b32_e32 v52, 0
	v_mov_b32_e32 v51, 0
	v_mov_b32_e32 v50, 0
	v_mov_b32_e32 v49, 0
	v_mov_b32_e32 v48, 0
	v_mov_b32_e32 v47, 0
	v_mov_b32_e32 v46, 0
	v_mov_b32_e32 v37, 0
	v_mov_b32_e32 v36, 0
	v_mov_b32_e32 v35, 0
	v_mov_b32_e32 v34, 0
	v_mov_b32_e32 v33, 0
	v_mov_b32_e32 v32, 0
	v_mov_b32_e32 v31, 0
	v_mov_b32_e32 v30, 0
	v_mov_b32_e32 v21, 0
	v_mov_b32_e32 v20, 0
	v_mov_b32_e32 v19, 0
	v_mov_b32_e32 v18, 0
	v_mov_b32_e32 v17, 0
	v_mov_b32_e32 v16, 0
	v_mov_b32_e32 v15, 0
	v_mov_b32_e32 v14, 0
	v_mov_b32_e32 v61, 0
	v_mov_b32_e32 v60, 0
	v_mov_b32_e32 v59, 0
	v_mov_b32_e32 v58, 0
	v_mov_b32_e32 v57, 0
	v_mov_b32_e32 v56, 0
	v_mov_b32_e32 v55, 0
	v_mov_b32_e32 v54, 0
	v_mov_b32_e32 v45, 0
	v_mov_b32_e32 v44, 0
	v_mov_b32_e32 v43, 0
	v_mov_b32_e32 v42, 0
	v_mov_b32_e32 v41, 0
	v_mov_b32_e32 v40, 0
	v_mov_b32_e32 v39, 0
	v_mov_b32_e32 v38, 0
	v_mov_b32_e32 v29, 0
	v_mov_b32_e32 v28, 0
	v_mov_b32_e32 v27, 0
	v_mov_b32_e32 v26, 0
	v_mov_b32_e32 v25, 0
	v_mov_b32_e32 v24, 0
	v_mov_b32_e32 v23, 0
	v_mov_b32_e32 v22, 0
	v_mov_b32_e32 v13, 0
	v_mov_b32_e32 v12, 0
	v_mov_b32_e32 v11, 0
	v_mov_b32_e32 v10, 0
	v_mov_b32_e32 v9, 0
	v_mov_b32_e32 v8, 0
	v_mov_b32_e32 v7, 0
	v_mov_b32_e32 v6, 0
	s_branch .LBB0_270

; #define PG8_STAGE(bufoff, gbase, voff) do { _Pragma("unroll") for (int _i = 0; _i < 2; ++_i) \
;         __builtin_amdgcn_global_load_lds((const unsigned*)((const char*)(gbase) + (voff)[_i]), (PG8_LAS unsigned*)(lds + (bufoff) + ldsw + _i * 8192), 16, 0, 0); } while (0)
; #define PG8_WAIT_V(n) asm volatile("s_waitcnt vmcnt(" #n ")" ::: "memory")
; #define PG8_BAR __builtin_amdgcn_s_barrier()
; template <class Epi, class Sched, bool ALIGN_EPI = false, bool SP2 = false, bool ACHUNK = false>
; __device__ __forceinline__ void gemm_phase(PG8_LAS unsigned char* lds, const Gemm g, const Sched& S, const Epi& E) {
;     ...
;     const int tid = tid_, wid = __builtin_amdgcn_readfirstlane(tid >> 6), lane = tid & 63, wr = wid >> 2, wc = wid & 3, fr = lane & 15, fq = lane >> 4;
;     int K_ = g.K; asm volatile("" : "+s"(K_));
;     const int K = K_, nt = K / BK;
;     unsigned voffA[2], voffB[2];
; #pragma unroll
;     for (int i = 0; i < 2; ++i) { int R, C; stage_rc(tid * 16 + i * 8192, R, C); const int Rb = Epi::PERM ? ((R & ~31) + perm32(R & 31)) : R;
;         const int Ra = ACHUNK ? ((R >> 6) * 62 + 4 * (R & 15) + ((R >> 4) & 3)) : R;     voffA[i] = (unsigned)(Ra * K + C) * 2u; voffB[i] = (unsigned)(Rb * K + C) * 2u; }
;     const size_t kstep = (size_t)(BK * 2);
;     const size_t hstepB = (size_t)HALF * K * 2, hstepA = ACHUNK ? (size_t)124 * K * 2 : hstepB;
;     const size_t tstepA = 2 * hstepA, tstepB = 2 * hstepB;
;     const unsigned ldsw = (unsigned)wid * 1024u;
;     const int aoff = lds_byte(wr * 64 + fr, fq * 8), boff = lds_byte(wc * 32 + fr, fq * 8);
;     ...
;     if constexpr (SP2) {
;         PG8_STAGE(PG8_SB(0, 0), cB, voffB); PG8_STAGE(PG8_SB(0, 1), cB + hstepB, voffB); PG8_STAGE(PG8_SA(0, 0), cA, voffA); PG8_STAGE(PG8_SA(0, 1), cA + hstepA, voffA);
;         if (wr == 1) PG8_BAR;
;         PG8_WAIT_V(2); PG8_BAR;
;         PG8_STAGE(PG8_SB(1, 0), cB + kstep, voffB); PG8_STAGE(PG8_SA(1, 0), cA + kstep, voffA); PG8_STAGE(PG8_SB(1, 1), cB + hstepB + kstep, voffB);
;         PG8_WAIT_V(6); PG8_BAR;
.LBB0_366:
	v_lshrrev_b32_e32 v22, 1, v141
	v_and_b32_e32 v22, 24, v22
	v_and_b32_e32 v21, 15, v141
	s_lshr_b32 s1, s1, 26
	v_lshlrev_b32_e32 v23, 1, v22
	s_add_i32 s1, s0, s1
	v_lshl_or_b32 v174, s9, 6, v21
	v_lshl_or_b32 v23, v21, 6, v23
	v_lshlrev_b32_e32 v21, 2, v21
	s_ashr_i32 s24, s1, 6
	s_lshl_b32 s1, s9, 13
	v_and_b32_e32 v24, 32, v21
	v_bitop3_b32 v25, v23, s1, v24 bitop3:0xde
	s_lshl_b32 s1, s25, 5
	s_and_b32 s1, s1, 0x60
	s_lshl_b32 s25, s1, 7
	s_add_i32 m0, s20, 0x18000
	v_lshl_add_u64 v[4:5], v[4:5], 0, s[10:11]
	v_bitop3_b32 v175, v23, s25, v24 bitop3:0xde
	s_waitcnt vmcnt(2)
	s_barrier
	global_load_lds_dwordx4 v[4:5], off
	v_lshl_add_u64 v[4:5], v[6:7], 0, s[10:11]
	s_add_i32 m0, s20, 0x1a000
	s_add_i32 s25, s20, 0x8000
	global_load_lds_dwordx4 v[4:5], off
	v_lshl_add_u64 v[4:5], v[12:13], 0, s[10:11]
	s_mov_b32 m0, s25
	s_add_i32 s26, s20, 0xa000
	global_load_lds_dwordx4 v[4:5], off
	v_lshl_add_u64 v[4:5], v[14:15], 0, s[10:11]
	s_mov_b32 m0, s26
	v_add_u32_e32 v2, v17, v2
	global_load_lds_dwordx4 v[4:5], off
	s_add_i32 m0, s20, 0x1c000
	v_lshl_add_u64 v[4:5], v[8:9], 0, s[10:11]
	global_load_lds_dwordx4 v[4:5], off
	v_lshl_add_u64 v[4:5], v[10:11], 0, s[10:11]
	s_add_i32 m0, s20, 0x1e000
	s_cmp_gt_i32 s0, 63
	global_load_lds_dwordx4 v[4:5], off
	s_cselect_b64 s[34:35], -1, 0
	s_lshl_b32 s0, s9, 8
	s_add_i32 s0, s0, 0
	s_add_i32 s0, s0, 0x20400
	s_add_i32 s27, s24, -2
	v_add_lshl_u32 v2, v2, v16, 1
	s_waitcnt vmcnt(6)
	s_cmpk_lt_u32 s8, 0x100
	v_lshl_add_u64 v[142:143], s[18:19], 0, v[2:3]
	v_add_u32_e32 v2, v20, v18
	v_add_u32_e32 v176, s0, v21
	s_cselect_b64 s[40:41], -1, 0
	s_add_i32 s0, 0, 0x25000
	v_or_b32_e32 v140, s1, v22
	v_add_lshl_u32 v2, v2, v19, 1
	s_add_i32 s36, s0, s13
	v_or_b32_e32 v177, 0xfffffb00, v140
	s_ashr_i32 s37, s50, 31
	v_lshl_add_u32 v178, v140, 2, s0
	v_lshl_add_u64 v[144:145], s[18:19], 0, v[2:3]
	s_mov_b32 s47, 0
	v_add_u32_e32 v179, 0, v25
	s_barrier
	s_nop 0
	s_branch .LBB0_369
